# GLA output-pass tail: loop-invariant onorm gains hoisted out of the chunk loop, store-completion waits removed; attention epilogue gate loads batched; adaLN norm loads batched
# speedup vs baseline: 1.0954x; 1.0114x over previous
.LBB0_28:
	v_mov_b32_e32 v0, v198
	s_ashr_i32 s10, s1, 11
	v_and_b32_e32 v21, 63, v0
	v_bfe_u32 v0, v0, 6, 2
	v_add_u32_e32 v10, s16, v0
	v_ashrrev_i32_e32 v11, 31, v10
	v_lshlrev_b64 v[0:1], 12, v[10:11]
	s_waitcnt lgkmcnt(0)
	v_lshl_add_u64 v[0:1], s[2:3], 0, v[0:1]
	v_lshlrev_b32_e32 v8, 4, v21
	v_lshl_add_u64 v[32:33], v[0:1], 0, v[8:9]
	global_load_dwordx4 v[24:27], v[32:33], off
	global_load_dwordx4 v[28:31], v[32:33], off offset:1024
	global_load_dwordx4 v[4:7], v[32:33], off offset:2048
	global_load_dwordx4 v[0:3], v[32:33], off offset:3072
	s_mulk_i32 s10, 0xc00
	s_ashr_i32 s11, s10, 31
	s_lshl_b64 s[10:11], s[10:11], 2
	s_add_u32 s10, s14, s10
	s_addc_u32 s11, s15, s11
	s_add_u32 s12, s10, 0x1000
	s_addc_u32 s13, s11, 0
	global_load_dwordx4 v[32:35], v8, s[12:13]
	global_load_dwordx4 v[36:39], v8, s[4:5]
	global_load_dwordx4 v[40:43], v8, s[10:11]
	v_or_b32_e32 v100, 0x400, v8
	v_or_b32_e32 v101, 0x800, v8
	v_or_b32_e32 v102, 0xc00, v8
	global_load_dwordx4 v[64:67], v8, s[4:5] offset:1024
	global_load_dwordx4 v[68:71], v100, s[12:13]
	global_load_dwordx4 v[72:75], v8, s[10:11] offset:1024
	global_load_dwordx4 v[76:79], v8, s[4:5] offset:2048
	global_load_dwordx4 v[80:83], v101, s[12:13]
	global_load_dwordx4 v[84:87], v8, s[10:11] offset:2048
	global_load_dwordx4 v[88:91], v8, s[4:5] offset:3072
	global_load_dwordx4 v[92:95], v102, s[12:13]
	global_load_dwordx4 v[96:99], v8, s[10:11] offset:3072
	v_cmp_lt_i32_e32 vcc, v14, v13
	s_waitcnt vmcnt(15)
	v_mov_b32_e32 v46, v25
	v_cndmask_b32_e32 v44, v12, v14, vcc
	s_waitcnt vmcnt(14)
	v_mov_b32_e32 v47, v29
	v_lshlrev_b32_e32 v60, 2, v44
	v_mov_b32_e32 v44, v24
	v_mov_b32_e32 v45, v28
	s_waitcnt vmcnt(13)
	v_mov_b32_e32 v54, v5
	s_waitcnt vmcnt(12)
	v_mov_b32_e32 v55, v1
	v_pk_mul_f32 v[46:47], v[46:47], v[46:47]
	v_mov_b32_e32 v48, v26
	v_mov_b32_e32 v49, v30
	v_mov_b32_e32 v52, v4
	v_mov_b32_e32 v53, v0
	v_pk_mul_f32 v[54:55], v[54:55], v[54:55]
	v_pk_fma_f32 v[44:45], v[44:45], v[44:45], v[46:47]
	v_mov_b32_e32 v50, v27
	v_mov_b32_e32 v51, v31
	v_mov_b32_e32 v56, v6
	v_mov_b32_e32 v57, v2
	v_pk_fma_f32 v[46:47], v[52:53], v[52:53], v[54:55]
	v_pk_fma_f32 v[44:45], v[48:49], v[48:49], v[44:45]
	v_mov_b32_e32 v58, v7
	v_mov_b32_e32 v59, v3
	v_pk_fma_f32 v[46:47], v[56:57], v[56:57], v[46:47]
	v_pk_fma_f32 v[44:45], v[50:51], v[50:51], v[44:45]
	v_pk_fma_f32 v[46:47], v[58:59], v[58:59], v[46:47]
	v_add_f32_e32 v44, v44, v45
	v_add_f32_e32 v44, v44, v46
	v_add_f32_e32 v44, v44, v47
	ds_bpermute_b32 v45, v60, v44
	v_cmp_lt_i32_e32 vcc, v15, v13
	s_waitcnt vmcnt(11)
	v_pk_add_f32 v[32:33], v[32:33], 1.0 op_sel_hi:[1,0]
	v_pk_add_f32 v[34:35], v[34:35], 1.0 op_sel_hi:[1,0]
	v_cndmask_b32_e32 v46, v12, v15, vcc
	v_lshlrev_b32_e32 v46, 2, v46
	s_waitcnt lgkmcnt(0)
	v_add_f32_e32 v44, v44, v45
	ds_bpermute_b32 v45, v46, v44
	v_cmp_lt_i32_e32 vcc, v16, v13
	v_or_b32_e32 v50, 0x400, v8
	s_waitcnt lgkmcnt(0)
	v_add_f32_e32 v44, v44, v45
	v_cndmask_b32_e32 v46, v12, v16, vcc
	v_lshlrev_b32_e32 v46, 2, v46
	ds_bpermute_b32 v45, v46, v44
	v_cmp_lt_i32_e32 vcc, v17, v13
	s_waitcnt lgkmcnt(0)
	v_add_f32_e32 v44, v44, v45
	v_cndmask_b32_e32 v46, v12, v17, vcc
	v_lshlrev_b32_e32 v46, 2, v46
	ds_bpermute_b32 v45, v46, v44
	v_cmp_lt_i32_e32 vcc, v18, v13
	s_waitcnt lgkmcnt(0)
	v_add_f32_e32 v44, v44, v45
	v_cndmask_b32_e32 v46, v12, v18, vcc
	v_lshlrev_b32_e32 v46, 2, v46
	ds_bpermute_b32 v46, v46, v44
	v_cmp_lt_i32_e32 vcc, v19, v13
	v_mov_b32_e32 v45, v9
	s_waitcnt lgkmcnt(0)
	v_add_f32_e32 v48, v44, v46
	v_cndmask_b32_e32 v47, v12, v19, vcc
	v_lshlrev_b32_e32 v47, 2, v47
	ds_bpermute_b32 v49, v47, v48
	v_lshlrev_b64 v[46:47], 11, v[10:11]
	v_lshlrev_b32_e32 v44, 3, v21
	v_lshl_add_u64 v[46:47], s[6:7], 0, v[46:47]
	v_lshl_add_u64 v[44:45], v[46:47], 0, v[44:45]
	s_waitcnt lgkmcnt(0)
	v_add_f32_e32 v11, v48, v49
	v_fmamk_f32 v11, v11, 0x3a800000, v20
	v_mul_f32_e32 v48, 0x4b800000, v11
	v_cmp_gt_f32_e32 vcc, s18, v11
	s_nop 1
	v_cndmask_b32_e32 v11, v11, v48, vcc
	v_rsq_f32_e32 v11, v11
	s_nop 0
	v_mul_f32_e32 v46, 0x45800000, v11
	v_cndmask_b32_e32 v46, v11, v46, vcc
	v_pk_mul_f32 v[24:25], v[24:25], v[46:47] op_sel_hi:[1,0]
	v_pk_mul_f32 v[26:27], v[26:27], v[46:47] op_sel_hi:[1,0]
	s_waitcnt vmcnt(10)
	v_pk_mul_f32 v[24:25], v[36:37], v[24:25]
	v_pk_mul_f32 v[26:27], v[38:39], v[26:27]
	s_waitcnt vmcnt(9)
	v_pk_fma_f32 v[24:25], v[32:33], v[24:25], v[40:41]
	v_pk_fma_f32 v[26:27], v[34:35], v[26:27], v[42:43]
	v_cvt_pk_bf16_f32 v24, v24, v25
	v_cvt_pk_bf16_f32 v25, v26, v27
	global_store_dwordx2 v[44:45], v[24:25], off
	v_pk_mul_f32 v[28:29], v[28:29], v[46:47] op_sel_hi:[1, 0]
	v_pk_mul_f32 v[30:31], v[30:31], v[46:47] op_sel_hi:[1, 0]
	v_or_b32_e32 v11, 0x800, v8
	v_pk_mul_f32 v[4:5], v[4:5], v[46:47] op_sel_hi:[1, 0]
	v_pk_mul_f32 v[6:7], v[6:7], v[46:47] op_sel_hi:[1, 0]
	v_pk_mul_f32 v[0:1], v[0:1], v[46:47] op_sel_hi:[1, 0]
	v_pk_mul_f32 v[2:3], v[2:3], v[46:47] op_sel_hi:[1, 0]
	v_cmp_eq_u32_e32 vcc, 0, v21
	s_waitcnt vmcnt(9)
	v_pk_mul_f32 v[24:25], v[64:65], v[28:29]
	s_waitcnt vmcnt(8)
	v_pk_add_f32 v[28:29], v[68:69], 1.0 op_sel_hi:[1, 0]
	v_pk_mul_f32 v[26:27], v[66:67], v[30:31]
	v_pk_add_f32 v[30:31], v[70:71], 1.0 op_sel_hi:[1, 0]
	s_waitcnt vmcnt(7)
	v_pk_fma_f32 v[24:25], v[28:29], v[24:25], v[72:73]
	v_pk_fma_f32 v[26:27], v[30:31], v[26:27], v[74:75]
	v_cvt_pk_bf16_f32 v24, v24, v25
	v_cvt_pk_bf16_f32 v25, v26, v27
	global_store_dwordx2 v[44:45], v[24:25], off offset:512
	v_or_b32_e32 v11, 0xc00, v8
	s_waitcnt vmcnt(7)
	v_pk_mul_f32 v[4:5], v[4:5], v[76:77]
	s_waitcnt vmcnt(6)
	v_pk_add_f32 v[24:25], v[80:81], 1.0 op_sel_hi:[1, 0]
	v_pk_mul_f32 v[6:7], v[6:7], v[78:79]
	v_pk_add_f32 v[26:27], v[82:83], 1.0 op_sel_hi:[1, 0]
	s_waitcnt vmcnt(5)
	v_pk_fma_f32 v[4:5], v[4:5], v[24:25], v[84:85]
	v_pk_fma_f32 v[6:7], v[6:7], v[26:27], v[86:87]
	v_cvt_pk_bf16_f32 v4, v4, v5
	v_cvt_pk_bf16_f32 v5, v6, v7
	global_store_dwordx2 v[44:45], v[4:5], off offset:1024
	s_waitcnt vmcnt(5)
	v_pk_mul_f32 v[0:1], v[0:1], v[88:89]
	s_waitcnt vmcnt(4)
	v_pk_add_f32 v[4:5], v[92:93], 1.0 op_sel_hi:[1, 0]
	v_pk_mul_f32 v[2:3], v[2:3], v[90:91]
	v_pk_add_f32 v[6:7], v[94:95], 1.0 op_sel_hi:[1, 0]
	s_waitcnt vmcnt(3)
	v_pk_fma_f32 v[0:1], v[0:1], v[4:5], v[96:97]
	v_pk_fma_f32 v[2:3], v[2:3], v[6:7], v[98:99]
	v_cvt_pk_bf16_f32 v0, v0, v1
	v_cvt_pk_bf16_f32 v1, v2, v3
	global_store_dwordx2 v[44:45], v[0:1], off offset:1536
	s_and_saveexec_b64 s[10:11], vcc
	s_cbranch_execz .LBB0_27
	v_lshlrev_b32_e32 v0, 1, v10
	v_ashrrev_i32_e32 v1, 31, v0
	v_lshl_add_u64 v[0:1], v[0:1], 2, s[8:9]
	global_store_dwordx2 v[0:1], v[22:23], off
	s_branch .LBB0_27

.LBB0_652:
	s_or_b64 exec, exec, s[10:11]
	ds_bpermute_b32 v0, v173, v215
	s_and_b64 vcc, exec, s[92:93]
	s_cbranch_vccz .LBB0_654
	s_waitcnt lgkmcnt(0)
	v_add_f32_e32 v0, v215, v0
	v_div_scale_f32 v2, s[2:3], v0, v0, 1.0
	v_rcp_f32_e32 v3, v2
	v_mov_b32_e32 v165, v1
	v_lshl_add_u64 v[4:5], v[156:157], 0, v[164:165]
	s_mov_b64 s[2:3], 0x1800
	v_fma_f32 v6, -v2, v3, 1.0
	v_fmac_f32_e32 v3, v6, v3
	v_div_scale_f32 v6, vcc, 1.0, v0, 1.0
	v_mul_f32_e32 v7, v6, v3
	v_fma_f32 v8, -v2, v7, v6
	v_fmac_f32_e32 v7, v8, v3
	v_fma_f32 v2, -v2, v7, v6
	v_div_fmas_f32 v2, v2, v3, v7
	v_div_fixup_f32 v2, v2, v0, 1.0
	v_lshlrev_b32_e32 v0, 1, v159
	v_lshl_add_u64 v[6:7], v[4:5], 0, v[0:1]
	v_lshl_add_u64 v[4:5], v[6:7], 0, s[2:3]
	v_add_co_u32_e32 v6, vcc, s78, v6
	v_pk_mul_f32 v[10:11], v[32:33], v[2:3] op_sel_hi:[1,0]
	s_nop 0
	v_addc_co_u32_e32 v7, vcc, 0, v7, vcc
	global_load_dwordx2 v[8:9], v[6:7], off offset:2048
	global_load_dwordx2 v[222:223], v[4:5], off offset:16
	global_load_dwordx2 v[224:225], v[4:5], off offset:32
	global_load_dwordx2 v[226:227], v[4:5], off offset:48
	global_load_dwordx2 v[228:229], v[4:5], off offset:64
	global_load_dwordx2 v[230:231], v[4:5], off offset:80
	global_load_dwordx2 v[232:233], v[4:5], off offset:96
	global_load_dwordx2 v[234:235], v[4:5], off offset:112
	s_waitcnt vmcnt(0)
	v_lshlrev_b32_e32 v12, 16, v8
	v_and_b32_e32 v13, 0xffff0000, v8
	v_pk_mul_f32 v[10:11], v[10:11], v[12:13]
	v_pk_mul_f32 v[12:13], v[34:35], v[2:3] op_sel_hi:[1,0]
	v_lshlrev_b32_e32 v8, 16, v9
	v_and_b32_e32 v9, 0xffff0000, v9
	v_pk_mul_f32 v[8:9], v[12:13], v[8:9]
	v_cvt_pk_bf16_f32 v10, v10, v11
	v_cvt_pk_bf16_f32 v11, v8, v9
	global_store_dwordx2 v[6:7], v[10:11], off offset:2048
	s_nop 1
	v_mov_b64_e32 v[6:7], v[222:223]
	v_pk_mul_f32 v[8:9], v[36:37], v[2:3] op_sel_hi:[1,0]
	v_lshlrev_b32_e32 v10, 16, v6
	v_and_b32_e32 v11, 0xffff0000, v6
	v_pk_mul_f32 v[8:9], v[8:9], v[10:11]
	v_pk_mul_f32 v[10:11], v[38:39], v[2:3] op_sel_hi:[1,0]
	v_lshlrev_b32_e32 v6, 16, v7
	v_and_b32_e32 v7, 0xffff0000, v7
	v_pk_mul_f32 v[6:7], v[10:11], v[6:7]
	v_cvt_pk_bf16_f32 v8, v8, v9
	v_cvt_pk_bf16_f32 v9, v6, v7
	s_nop 1
	v_mov_b64_e32 v[6:7], v[224:225]
	v_lshlrev_b32_e32 v10, 16, v6
	global_store_dwordx2 v[4:5], v[8:9], off offset:16
	v_pk_mul_f32 v[8:9], v[40:41], v[2:3] op_sel_hi:[1,0]
	v_and_b32_e32 v11, 0xffff0000, v6
	v_pk_mul_f32 v[8:9], v[8:9], v[10:11]
	v_pk_mul_f32 v[10:11], v[42:43], v[2:3] op_sel_hi:[1,0]
	v_lshlrev_b32_e32 v6, 16, v7
	v_and_b32_e32 v7, 0xffff0000, v7
	v_pk_mul_f32 v[6:7], v[10:11], v[6:7]
	v_cvt_pk_bf16_f32 v8, v8, v9
	v_cvt_pk_bf16_f32 v9, v6, v7
	s_nop 1
	v_mov_b64_e32 v[6:7], v[226:227]
	v_lshlrev_b32_e32 v10, 16, v6
	global_store_dwordx2 v[4:5], v[8:9], off offset:32
	v_pk_mul_f32 v[8:9], v[44:45], v[2:3] op_sel_hi:[1,0]
	v_and_b32_e32 v11, 0xffff0000, v6
	v_pk_mul_f32 v[8:9], v[8:9], v[10:11]
	v_pk_mul_f32 v[10:11], v[46:47], v[2:3] op_sel_hi:[1,0]
	v_lshlrev_b32_e32 v6, 16, v7
	v_and_b32_e32 v7, 0xffff0000, v7
	v_pk_mul_f32 v[6:7], v[10:11], v[6:7]
	v_cvt_pk_bf16_f32 v8, v8, v9
	v_cvt_pk_bf16_f32 v9, v6, v7
	s_nop 1
	v_mov_b64_e32 v[6:7], v[228:229]
	v_lshlrev_b32_e32 v10, 16, v6
	global_store_dwordx2 v[4:5], v[8:9], off offset:48
	v_pk_mul_f32 v[8:9], v[16:17], v[2:3] op_sel_hi:[1,0]
	v_and_b32_e32 v11, 0xffff0000, v6
	v_pk_mul_f32 v[8:9], v[8:9], v[10:11]
	v_pk_mul_f32 v[10:11], v[18:19], v[2:3] op_sel_hi:[1,0]
	v_lshlrev_b32_e32 v6, 16, v7
	v_and_b32_e32 v7, 0xffff0000, v7
	v_pk_mul_f32 v[6:7], v[10:11], v[6:7]
	v_cvt_pk_bf16_f32 v8, v8, v9
	v_cvt_pk_bf16_f32 v9, v6, v7
	s_nop 1
	v_mov_b64_e32 v[6:7], v[230:231]
	v_lshlrev_b32_e32 v10, 16, v6
	global_store_dwordx2 v[4:5], v[8:9], off offset:64
	v_pk_mul_f32 v[8:9], v[20:21], v[2:3] op_sel_hi:[1,0]
	v_and_b32_e32 v11, 0xffff0000, v6
	v_pk_mul_f32 v[8:9], v[8:9], v[10:11]
	v_pk_mul_f32 v[10:11], v[22:23], v[2:3] op_sel_hi:[1,0]
	v_lshlrev_b32_e32 v6, 16, v7
	v_and_b32_e32 v7, 0xffff0000, v7
	v_pk_mul_f32 v[6:7], v[10:11], v[6:7]
	v_cvt_pk_bf16_f32 v8, v8, v9
	v_cvt_pk_bf16_f32 v9, v6, v7
	s_nop 1
	v_mov_b64_e32 v[6:7], v[232:233]
	v_lshlrev_b32_e32 v10, 16, v6
	global_store_dwordx2 v[4:5], v[8:9], off offset:80
	v_pk_mul_f32 v[8:9], v[24:25], v[2:3] op_sel_hi:[1,0]
	v_and_b32_e32 v11, 0xffff0000, v6
	v_pk_mul_f32 v[8:9], v[8:9], v[10:11]
	v_pk_mul_f32 v[10:11], v[26:27], v[2:3] op_sel_hi:[1,0]
	v_lshlrev_b32_e32 v6, 16, v7
	v_and_b32_e32 v7, 0xffff0000, v7
	v_pk_mul_f32 v[6:7], v[10:11], v[6:7]
	v_cvt_pk_bf16_f32 v8, v8, v9
	v_cvt_pk_bf16_f32 v9, v6, v7
	s_nop 1
	v_mov_b64_e32 v[6:7], v[234:235]
	v_lshlrev_b32_e32 v10, 16, v6
	global_store_dwordx2 v[4:5], v[8:9], off offset:96
	v_pk_mul_f32 v[8:9], v[28:29], v[2:3] op_sel_hi:[1,0]
	v_and_b32_e32 v11, 0xffff0000, v6
	v_pk_mul_f32 v[2:3], v[30:31], v[2:3] op_sel_hi:[1,0]
	v_lshlrev_b32_e32 v6, 16, v7
	v_and_b32_e32 v7, 0xffff0000, v7
	v_pk_mul_f32 v[8:9], v[8:9], v[10:11]
	v_pk_mul_f32 v[2:3], v[2:3], v[6:7]
	v_cvt_pk_bf16_f32 v6, v8, v9
	v_cvt_pk_bf16_f32 v7, v2, v3
	global_store_dwordx2 v[4:5], v[6:7], off offset:112

.LBB0_692:
	s_or_b64 exec, exec, s[2:3]
	v_lshlrev_b32_e32 v66, 3, v99
	v_lshlrev_b32_e32 v0, 9, v100
	v_and_b32_e32 v66, 0x180, v66
	s_movk_i32 s2, 0xe000
	v_and_b32_e32 v68, 0x7f, v94
	v_and_or_b32 v67, v98, s2, v0
	v_or_b32_e32 v70, v68, v66
	v_readlane_b32 s2, v240, 49
	v_lshlrev_b32_e32 v0, 2, v70
	v_readlane_b32 s3, v240, 50
	v_mov_b64_e32 v[72:73], s[72:73]
	v_and_b32_e32 v69, 31, v94
	v_readlane_b32 s40, v240, 0
	v_readlane_b32 s41, v240, 1
	s_load_dwordx2 s[40:41], s[40:41], 0x40
	global_load_dword v128, v0, s[2:3]
	v_lshrrev_b32_e32 v0, 3, v94
	v_and_b32_e32 v71, 16, v0
	v_or_b32_e32 v129, v71, v67
	v_mad_i64_i32 v[74:75], s[2:3], v129, s77, v[72:73]
	v_lshlrev_b32_e32 v0, 1, v70
	v_lshl_add_u64 v[76:77], v[74:75], 0, v[0:1]
	global_load_ushort v130, v[76:77], off
	global_load_ushort v131, v[76:77], off offset:1024
	v_or_b32_e32 v76, 1, v129
	v_mad_i64_i32 v[76:77], s[2:3], v76, s77, v[72:73]
	v_lshl_add_u64 v[78:79], v[76:77], 0, v[0:1]
	global_load_ushort v132, v[78:79], off
	global_load_ushort v133, v[78:79], off offset:1024
	v_or_b32_e32 v78, 2, v129
	v_mad_i64_i32 v[78:79], s[2:3], v78, s77, v[72:73]
	v_lshl_add_u64 v[80:81], v[78:79], 0, v[0:1]
	global_load_ushort v134, v[80:81], off
	global_load_ushort v135, v[80:81], off offset:1024
	v_or_b32_e32 v80, 3, v129
	v_mad_i64_i32 v[80:81], s[2:3], v80, s77, v[72:73]
	v_lshl_add_u64 v[82:83], v[80:81], 0, v[0:1]
	global_load_ushort v136, v[82:83], off
	global_load_ushort v137, v[82:83], off offset:1024
	v_or_b32_e32 v82, 4, v129
	v_mad_i64_i32 v[82:83], s[2:3], v82, s77, v[72:73]
	v_lshl_add_u64 v[84:85], v[82:83], 0, v[0:1]
	global_load_ushort v138, v[84:85], off
	global_load_ushort v139, v[84:85], off offset:1024
	v_or_b32_e32 v84, 5, v129
	v_mad_i64_i32 v[84:85], s[2:3], v84, s77, v[72:73]
	v_lshl_add_u64 v[86:87], v[84:85], 0, v[0:1]
	global_load_ushort v140, v[86:87], off
	global_load_ushort v141, v[86:87], off offset:1024
	v_or_b32_e32 v86, 6, v129
	v_mad_i64_i32 v[86:87], s[2:3], v86, s77, v[72:73]
	v_lshl_add_u64 v[88:89], v[86:87], 0, v[0:1]
	global_load_ushort v142, v[88:89], off
	global_load_ushort v143, v[88:89], off offset:1024
	v_or_b32_e32 v88, 7, v129
	v_mad_i64_i32 v[88:89], s[2:3], v88, s77, v[72:73]
	v_lshl_add_u64 v[90:91], v[88:89], 0, v[0:1]
	global_load_ushort v144, v[90:91], off
	global_load_ushort v145, v[90:91], off offset:1024
	v_or_b32_e32 v90, 8, v129
	v_mad_i64_i32 v[90:91], s[2:3], v90, s77, v[72:73]
	v_lshl_add_u64 v[92:93], v[90:91], 0, v[0:1]
	global_load_ushort v146, v[92:93], off
	global_load_ushort v147, v[92:93], off offset:1024
	v_or_b32_e32 v92, 9, v129
	v_mad_i64_i32 v[92:93], s[2:3], v92, s77, v[72:73]
	v_lshl_add_u64 v[98:99], v[92:93], 0, v[0:1]
	global_load_ushort v148, v[98:99], off
	global_load_ushort v149, v[98:99], off offset:1024
	v_or_b32_e32 v98, 10, v129
	v_mad_i64_i32 v[98:99], s[2:3], v98, s77, v[72:73]
	v_lshl_add_u64 v[100:101], v[98:99], 0, v[0:1]
	global_load_ushort v150, v[100:101], off
	global_load_ushort v151, v[100:101], off offset:1024
	v_or_b32_e32 v100, 11, v129
	v_mad_i64_i32 v[100:101], s[2:3], v100, s77, v[72:73]
	v_lshl_add_u64 v[102:103], v[100:101], 0, v[0:1]
	global_load_ushort v152, v[102:103], off
	global_load_ushort v153, v[102:103], off offset:1024
	v_or_b32_e32 v102, 12, v129
	v_mad_i64_i32 v[102:103], s[2:3], v102, s77, v[72:73]
	v_lshl_add_u64 v[104:105], v[102:103], 0, v[0:1]
	global_load_ushort v154, v[104:105], off
	global_load_ushort v155, v[104:105], off offset:1024
	v_or_b32_e32 v104, 13, v129
	v_mad_i64_i32 v[104:105], s[2:3], v104, s77, v[72:73]
	v_lshl_add_u64 v[106:107], v[104:105], 0, v[0:1]
	global_load_ushort v156, v[106:107], off
	global_load_ushort v158, v[106:107], off offset:1024
	v_or_b32_e32 v106, 14, v129
	v_mad_i64_i32 v[106:107], s[2:3], v106, s77, v[72:73]
	v_lshl_add_u64 v[108:109], v[106:107], 0, v[0:1]
	global_load_ushort v162, v[108:109], off
	global_load_ushort v163, v[108:109], off offset:1024
	v_or_b32_e32 v108, 15, v129
	v_mad_i64_i32 v[72:73], s[2:3], v108, s77, v[72:73]
	v_lshl_add_u64 v[108:109], v[72:73], 0, v[0:1]
	v_lshlrev_b32_e32 v0, 1, v66
	global_load_ushort v166, v[108:109], off
	global_load_ushort v167, v[108:109], off offset:1024
	v_lshl_add_u64 v[74:75], v[74:75], 0, v[0:1]
	v_lshlrev_b32_e32 v108, 1, v68
	v_mov_b32_e32 v109, v1
	v_lshl_add_u64 v[72:73], v[72:73], 0, v[0:1]
	v_lshl_add_u64 v[74:75], v[74:75], 0, v[108:109]
	v_lshl_add_u64 v[72:73], v[72:73], 0, v[108:109]
	global_load_ushort v174, v[74:75], off offset:2048
	global_load_ushort v115, v[72:73], off offset:2048
	v_lshl_add_u64 v[74:75], v[76:77], 0, v[0:1]
	v_lshl_add_u64 v[74:75], v[74:75], 0, v[108:109]
	global_load_ushort v175, v[74:75], off offset:2048
	v_lshl_add_u64 v[74:75], v[78:79], 0, v[0:1]
	v_lshl_add_u64 v[74:75], v[74:75], 0, v[108:109]
	global_load_ushort v176, v[74:75], off offset:2048
	v_lshl_add_u64 v[74:75], v[80:81], 0, v[0:1]
	v_lshl_add_u64 v[74:75], v[74:75], 0, v[108:109]
	global_load_ushort v177, v[74:75], off offset:2048
	v_lshl_add_u64 v[74:75], v[82:83], 0, v[0:1]
	v_lshl_add_u64 v[74:75], v[74:75], 0, v[108:109]
	global_load_ushort v178, v[74:75], off offset:2048
	v_lshl_add_u64 v[74:75], v[84:85], 0, v[0:1]
	v_lshl_add_u64 v[74:75], v[74:75], 0, v[108:109]
	global_load_ushort v179, v[74:75], off offset:2048
	v_lshl_add_u64 v[74:75], v[86:87], 0, v[0:1]
	v_lshl_add_u64 v[74:75], v[74:75], 0, v[108:109]
	global_load_ushort v180, v[74:75], off offset:2048
	v_lshl_add_u64 v[74:75], v[88:89], 0, v[0:1]
	v_lshl_add_u64 v[74:75], v[74:75], 0, v[108:109]
	global_load_ushort v181, v[74:75], off offset:2048
	v_lshl_add_u64 v[74:75], v[90:91], 0, v[0:1]
	v_lshl_add_u64 v[74:75], v[74:75], 0, v[108:109]
	global_load_ushort v182, v[74:75], off offset:2048
	v_lshl_add_u64 v[74:75], v[92:93], 0, v[0:1]
	v_lshl_add_u64 v[74:75], v[74:75], 0, v[108:109]
	global_load_ushort v183, v[74:75], off offset:2048
	v_lshl_add_u64 v[74:75], v[98:99], 0, v[0:1]
	v_lshl_add_u64 v[74:75], v[74:75], 0, v[108:109]
	global_load_ushort v184, v[74:75], off offset:2048
	v_lshl_add_u64 v[74:75], v[100:101], 0, v[0:1]
	v_lshl_add_u64 v[74:75], v[74:75], 0, v[108:109]
	global_load_ushort v185, v[74:75], off offset:2048
	v_lshl_add_u64 v[74:75], v[102:103], 0, v[0:1]
	v_lshl_add_u64 v[74:75], v[74:75], 0, v[108:109]
	global_load_ushort v186, v[74:75], off offset:2048
	v_lshl_add_u64 v[74:75], v[104:105], 0, v[0:1]
	v_lshl_add_u64 v[74:75], v[74:75], 0, v[108:109]
	global_load_ushort v187, v[74:75], off offset:2048
	v_lshl_add_u64 v[74:75], v[106:107], 0, v[0:1]
	v_lshl_add_u64 v[74:75], v[74:75], 0, v[108:109]
	global_load_ushort v188, v[74:75], off offset:2048
	v_mul_u32_u24_e32 v72, 40, v68
	v_lshl_add_u32 v77, v72, 1, s54
	v_lshl_add_u64 v[72:73], s[72:73], 0, v[0:1]
	v_lshrrev_b32_e32 v0, 1, v94
	v_and_b32_e32 v78, 0x60, v0
	v_mov_b32_e32 v76, s54
	v_lshlrev_b32_e32 v0, 1, v78
	v_or_b32_e32 v79, v78, v69
	v_lshl_add_u64 v[74:75], v[72:73], 0, v[0:1]
	v_lshlrev_b32_e32 v0, 1, v96
	v_mad_u32_u24 v76, v79, s90, v76
	v_and_b32_e32 v81, 64, v202
	v_lshl_add_u64 v[108:109], v[74:75], 0, v[0:1]
	v_add_u32_e32 v161, v76, v0
	v_xor_b32_e32 v0, 32, v202
	v_add_u32_e32 v81, 64, v81
	v_cmp_lt_i32_e32 vcc, v0, v81
	v_mul_u32_u24_e32 v74, 0x88, v69
	v_or_b32_e32 v78, v96, v78
	v_cndmask_b32_e32 v0, v202, v0, vcc
	v_lshlrev_b32_e32 v164, 2, v0
	v_mul_u32_u24_e32 v0, 0x88, v71
	v_or_b32_e32 v0, v0, v68
	v_lshl_add_u32 v165, v0, 1, s54
	v_or_b32_e32 v0, 2, v96
	v_cmp_gt_u32_e64 s[10:11], v0, v69
	v_or_b32_e32 v0, 3, v96
	v_cmp_gt_u32_e64 s[12:13], v0, v69
	v_or_b32_e32 v0, 8, v96
	v_cmp_gt_u32_e64 s[14:15], v0, v69
	v_or_b32_e32 v0, 9, v96
	v_cmp_gt_u32_e64 s[16:17], v0, v69
	v_or_b32_e32 v0, 10, v96
	v_cmp_gt_u32_e64 s[18:19], v0, v69
	v_or_b32_e32 v0, 11, v96
	v_cmp_gt_u32_e64 s[20:21], v0, v69
	v_or_b32_e32 v0, 16, v96
	v_cmp_gt_u32_e64 s[22:23], v0, v69
	v_or_b32_e32 v0, 17, v96
	v_cmp_gt_u32_e64 s[24:25], v0, v69
	v_or_b32_e32 v0, 18, v96
	v_cmp_gt_u32_e64 s[26:27], v0, v69
	v_or_b32_e32 v0, 19, v96
	v_cmp_gt_u32_e64 s[28:29], v0, v69
	v_or_b32_e32 v0, 24, v96
	v_cmp_gt_u32_e64 s[30:31], v0, v69
	v_or_b32_e32 v0, 25, v96
	v_cmp_gt_u32_e64 s[34:35], v0, v69
	v_or_b32_e32 v0, 26, v96
	v_cmp_gt_u32_e64 s[36:37], v0, v69
	v_or_b32_e32 v0, 27, v96
	v_lshl_add_u32 v74, v74, 1, s54
	v_lshlrev_b32_e32 v159, 3, v97
	v_lshlrev_b32_e32 v75, 4, v97
	v_cmp_gt_u32_e64 s[38:39], v0, v69
	v_lshlrev_b32_e32 v0, 2, v78
	s_waitcnt vmcnt(48)
	v_sub_f32_e32 v106, 1.0, v128
	v_lshl_add_u32 v157, v71, 1, v77
	s_movk_i32 s2, 0x80
	v_add_u32_e32 v160, v74, v75
	v_sub_u32_e32 v80, 0, v159
	v_add_u32_e32 v75, s54, v75
	v_mul_i32_i24_e32 v81, 0xfffffef4, v69
	v_mul_i32_i24_e32 v82, 0xffffffb4, v68
	v_mul_i32_i24_e32 v79, 0xffffffb4, v79
	v_mul_u32_u24_e32 v71, 0x50, v69
	s_waitcnt lgkmcnt(0)
	v_lshl_add_u64 v[110:111], s[40:41], 0, v[0:1]
	v_lshlrev_b32_e32 v0, 1, v78
	v_cmp_gt_u32_e64 s[2:3], s2, v95
	s_mov_b32 s52, 0
	v_cmp_eq_u32_e64 s[4:5], 0, v97
	v_cmp_gt_u32_e64 s[6:7], v96, v69
	v_cmp_lt_u32_e64 s[8:9], v96, v69
	v_mov_b32_e32 v107, v106
	v_lshl_add_u64 v[112:113], v[72:73], 0, v[0:1]
	v_or_b32_e32 v168, v67, v69
	v_lshlrev_b32_e32 v0, 1, v70
	v_lshlrev_b32_e32 v114, 1, v66
	v_lshlrev_b32_e32 v116, 1, v68
	v_add_u32_e32 v169, v160, v80
	v_add_u32_e32 v170, v75, v71
	v_add_u32_e32 v171, v76, v79
	v_add_u32_e32 v172, v74, v81
	v_add_u32_e32 v173, v77, v82
	global_load_dwordx4 v[222:225], v[110:111], off
	global_load_dwordx4 v[226:229], v[110:111], off offset:32
	global_load_dwordx4 v[230:233], v[110:111], off offset:64
	global_load_dwordx4 v[234:237], v[110:111], off offset:96
	s_branch .LBB0_695

.LBB0_701:
	v_add_u32_e32 v84, 0xbc00, v172
	ds_read2_b32 v[82:83], v84 offset1:32
	v_mad_i64_i32 v[88:89], s[40:41], v117, s77, 0
	s_waitcnt lgkmcnt(0)
	v_add_f32_e32 v85, v82, v83
	ds_read2_b32 v[82:83], v84 offset0:64 offset1:96
	s_waitcnt lgkmcnt(0)
	v_add_f32_e32 v82, v85, v82
	v_mov_b64_e32 v[84:85], v[222:223]
	v_mov_b64_e32 v[86:87], v[224:225]
	v_add_f32_e32 v82, v82, v83
	v_fmamk_f32 v82, v82, 0x3c000000, v201
	v_cmp_gt_f32_e32 vcc, s82, v82
	v_mul_f32_e32 v83, 0x4b800000, v82
	s_nop 0
	v_cndmask_b32_e32 v82, v82, v83, vcc
	v_rsq_f32_e32 v82, v82
	s_nop 0
	v_mul_f32_e32 v83, 0x45800000, v82
	v_cndmask_b32_e32 v82, v82, v83, vcc
	v_pk_mul_f32 v[66:67], v[66:67], v[82:83] op_sel_hi:[1,0]
	v_pk_mul_f32 v[68:69], v[68:69], v[82:83] op_sel_hi:[1,0]
	v_pk_mul_f32 v[70:71], v[70:71], v[82:83] op_sel_hi:[1,0]
	s_waitcnt vmcnt(0)
	v_pk_mul_f32 v[66:67], v[84:85], v[66:67]
	v_lshlrev_b32_e32 v84, 16, v124
	v_and_b32_e32 v85, 0xffff0000, v124
	v_pk_mul_f32 v[66:67], v[66:67], v[84:85]
	v_pk_mul_f32 v[68:69], v[86:87], v[68:69]
	v_lshlrev_b32_e32 v84, 16, v125
	v_and_b32_e32 v85, 0xffff0000, v125
	v_pk_mul_f32 v[68:69], v[68:69], v[84:85]
	v_cvt_pk_bf16_f32 v66, v66, v67
	v_cvt_pk_bf16_f32 v67, v68, v69
	v_lshl_add_u64 v[84:85], v[112:113], 0, v[88:89]
	global_store_dwordx2 v[84:85], v[66:67], off offset:3072
	v_mov_b64_e32 v[66:67], v[226:227]
	v_mov_b64_e32 v[68:69], v[228:229]
	v_pk_mul_f32 v[66:67], v[66:67], v[70:71]
	v_lshlrev_b32_e32 v70, 16, v122
	v_and_b32_e32 v71, 0xffff0000, v122
	v_pk_mul_f32 v[66:67], v[66:67], v[70:71]
	v_pk_mul_f32 v[70:71], v[72:73], v[82:83] op_sel_hi:[1,0]
	v_cvt_pk_bf16_f32 v66, v66, v67
	v_pk_mul_f32 v[68:69], v[70:71], v[68:69]
	v_lshlrev_b32_e32 v70, 16, v123
	v_and_b32_e32 v71, 0xffff0000, v123
	v_pk_mul_f32 v[68:69], v[68:69], v[70:71]
	v_pk_mul_f32 v[70:71], v[74:75], v[82:83] op_sel_hi:[1,0]
	v_cvt_pk_bf16_f32 v67, v68, v69
	global_store_dwordx2 v[84:85], v[66:67], off offset:3088
	v_mov_b64_e32 v[66:67], v[230:231]
	v_mov_b64_e32 v[68:69], v[232:233]
	v_pk_mul_f32 v[66:67], v[70:71], v[66:67]
	v_lshlrev_b32_e32 v70, 16, v120
	v_and_b32_e32 v71, 0xffff0000, v120
	v_pk_mul_f32 v[66:67], v[66:67], v[70:71]
	v_pk_mul_f32 v[70:71], v[76:77], v[82:83] op_sel_hi:[1,0]
	v_cvt_pk_bf16_f32 v66, v66, v67
	v_pk_mul_f32 v[68:69], v[70:71], v[68:69]
	v_lshlrev_b32_e32 v70, 16, v121
	v_and_b32_e32 v71, 0xffff0000, v121
	v_pk_mul_f32 v[68:69], v[68:69], v[70:71]
	v_pk_mul_f32 v[70:71], v[78:79], v[82:83] op_sel_hi:[1,0]
	v_cvt_pk_bf16_f32 v67, v68, v69
	global_store_dwordx2 v[84:85], v[66:67], off offset:3104
	v_mov_b64_e32 v[66:67], v[234:235]
	v_mov_b64_e32 v[68:69], v[236:237]
	v_pk_mul_f32 v[66:67], v[70:71], v[66:67]
	v_lshlrev_b32_e32 v70, 16, v118
	v_and_b32_e32 v71, 0xffff0000, v118
	v_pk_mul_f32 v[66:67], v[66:67], v[70:71]
	v_pk_mul_f32 v[70:71], v[80:81], v[82:83] op_sel_hi:[1,0]
	v_cvt_pk_bf16_f32 v66, v66, v67
	v_pk_mul_f32 v[68:69], v[70:71], v[68:69]
	v_lshlrev_b32_e32 v70, 16, v119
	v_and_b32_e32 v71, 0xffff0000, v119
	v_pk_mul_f32 v[68:69], v[68:69], v[70:71]
	s_nop 0
	v_cvt_pk_bf16_f32 v67, v68, v69
	global_store_dwordx2 v[84:85], v[66:67], off offset:3120
	s_add_i32 s52, s52, 32
	s_cmpk_lg_i32 s52, 0x200
	s_cbranch_scc1 .LBB0_695

.LBB0_794:
	v_mov_b32_e32 v0, v198
	s_ashr_i32 s8, s1, 11
	v_and_b32_e32 v17, 63, v0
	v_bfe_u32 v0, v0, 6, 2
	v_add_u32_e32 v6, s14, v0
	v_ashrrev_i32_e32 v7, 31, v6
	v_lshlrev_b64 v[0:1], 12, v[6:7]
	v_lshl_add_u64 v[0:1], s[52:53], 0, v[0:1]
	v_lshlrev_b32_e32 v4, 4, v17
	v_lshl_add_u64 v[0:1], v[0:1], 0, v[4:5]
	global_load_dwordx4 v[20:23], v[0:1], off
	global_load_dwordx4 v[24:27], v[0:1], off offset:1024
	global_load_dwordx4 v[28:31], v[0:1], off offset:2048
	s_nop 0
	global_load_dwordx4 v[0:3], v[0:1], off offset:3072
	s_mulk_i32 s8, 0xc00
	s_addk_i32 s8, 0x1800
	s_ashr_i32 s9, s8, 31
	s_lshl_b64 s[8:9], s[8:9], 2
	s_add_u32 s8, s12, s8
	s_addc_u32 s9, s13, s9
	s_add_u32 s10, s8, 0x1000
	s_addc_u32 s11, s9, 0
	global_load_dwordx4 v[32:35], v4, s[10:11]
	global_load_dwordx4 v[36:39], v4, s[4:5]
	global_load_dwordx4 v[40:43], v4, s[8:9]
	v_or_b32_e32 v100, 0x400, v4
	v_or_b32_e32 v101, 0x800, v4
	v_or_b32_e32 v102, 0xc00, v4
	global_load_dwordx4 v[64:67], v100, s[4:5]
	global_load_dwordx4 v[68:71], v100, s[10:11]
	global_load_dwordx4 v[72:75], v4, s[8:9] offset:1024
	global_load_dwordx4 v[76:79], v101, s[4:5]
	global_load_dwordx4 v[80:83], v101, s[10:11]
	global_load_dwordx4 v[84:87], v4, s[8:9] offset:2048
	global_load_dwordx4 v[88:91], v102, s[4:5]
	global_load_dwordx4 v[92:95], v102, s[10:11]
	global_load_dwordx4 v[96:99], v4, s[8:9] offset:3072
	v_cmp_lt_i32_e32 vcc, v10, v9
	s_waitcnt vmcnt(15)
	v_mov_b32_e32 v46, v21
	v_cndmask_b32_e32 v44, v8, v10, vcc
	s_waitcnt vmcnt(14)
	v_mov_b32_e32 v47, v25
	v_lshlrev_b32_e32 v60, 2, v44
	v_mov_b32_e32 v44, v20
	v_mov_b32_e32 v45, v24
	s_waitcnt vmcnt(13)
	v_mov_b32_e32 v54, v29
	s_waitcnt vmcnt(12)
	v_mov_b32_e32 v55, v1
	v_pk_mul_f32 v[46:47], v[46:47], v[46:47]
	v_mov_b32_e32 v48, v22
	v_mov_b32_e32 v49, v26
	v_mov_b32_e32 v52, v28
	v_mov_b32_e32 v53, v0
	v_pk_mul_f32 v[54:55], v[54:55], v[54:55]
	v_pk_fma_f32 v[44:45], v[44:45], v[44:45], v[46:47]
	v_mov_b32_e32 v50, v23
	v_mov_b32_e32 v51, v27
	v_mov_b32_e32 v56, v30
	v_mov_b32_e32 v57, v2
	v_pk_fma_f32 v[46:47], v[52:53], v[52:53], v[54:55]
	v_pk_fma_f32 v[44:45], v[48:49], v[48:49], v[44:45]
	v_mov_b32_e32 v58, v31
	v_mov_b32_e32 v59, v3
	v_pk_fma_f32 v[46:47], v[56:57], v[56:57], v[46:47]
	v_pk_fma_f32 v[44:45], v[50:51], v[50:51], v[44:45]
	v_pk_fma_f32 v[46:47], v[58:59], v[58:59], v[46:47]
	v_add_f32_e32 v44, v44, v45
	v_add_f32_e32 v44, v44, v46
	v_add_f32_e32 v44, v44, v47
	ds_bpermute_b32 v45, v60, v44
	v_cmp_lt_i32_e32 vcc, v11, v9
	s_waitcnt vmcnt(11)
	v_pk_add_f32 v[32:33], v[32:33], 1.0 op_sel_hi:[1,0]
	v_pk_add_f32 v[34:35], v[34:35], 1.0 op_sel_hi:[1,0]
	v_cndmask_b32_e32 v46, v8, v11, vcc
	v_lshlrev_b32_e32 v46, 2, v46
	s_waitcnt lgkmcnt(0)
	v_add_f32_e32 v44, v44, v45
	ds_bpermute_b32 v45, v46, v44
	v_cmp_lt_i32_e32 vcc, v12, v9
	v_or_b32_e32 v50, 0x400, v4
	s_waitcnt lgkmcnt(0)
	v_add_f32_e32 v44, v44, v45
	v_cndmask_b32_e32 v46, v8, v12, vcc
	v_lshlrev_b32_e32 v46, 2, v46
	ds_bpermute_b32 v45, v46, v44
	v_cmp_lt_i32_e32 vcc, v13, v9
	s_waitcnt lgkmcnt(0)
	v_add_f32_e32 v44, v44, v45
	v_cndmask_b32_e32 v46, v8, v13, vcc
	v_lshlrev_b32_e32 v46, 2, v46
	ds_bpermute_b32 v45, v46, v44
	v_cmp_lt_i32_e32 vcc, v14, v9
	s_waitcnt lgkmcnt(0)
	v_add_f32_e32 v44, v44, v45
	v_cndmask_b32_e32 v46, v8, v14, vcc
	v_lshlrev_b32_e32 v46, 2, v46
	ds_bpermute_b32 v46, v46, v44
	v_cmp_lt_i32_e32 vcc, v15, v9
	v_mov_b32_e32 v45, v5
	s_waitcnt lgkmcnt(0)
	v_add_f32_e32 v48, v44, v46
	v_cndmask_b32_e32 v47, v8, v15, vcc
	v_lshlrev_b32_e32 v47, 2, v47
	ds_bpermute_b32 v49, v47, v48
	v_lshlrev_b64 v[46:47], 11, v[6:7]
	v_lshlrev_b32_e32 v44, 3, v17
	v_lshl_add_u64 v[46:47], s[2:3], 0, v[46:47]
	v_lshl_add_u64 v[44:45], v[46:47], 0, v[44:45]
	s_waitcnt lgkmcnt(0)
	v_add_f32_e32 v7, v48, v49
	v_fmamk_f32 v7, v7, 0x3a800000, v16
	v_mul_f32_e32 v48, 0x4b800000, v7
	v_cmp_gt_f32_e32 vcc, s16, v7
	s_nop 1
	v_cndmask_b32_e32 v7, v7, v48, vcc
	v_rsq_f32_e32 v7, v7
	s_nop 0
	v_mul_f32_e32 v46, 0x45800000, v7
	v_cndmask_b32_e32 v46, v7, v46, vcc
	v_pk_mul_f32 v[20:21], v[20:21], v[46:47] op_sel_hi:[1,0]
	v_pk_mul_f32 v[22:23], v[22:23], v[46:47] op_sel_hi:[1,0]
	s_waitcnt vmcnt(10)
	v_pk_mul_f32 v[20:21], v[36:37], v[20:21]
	v_pk_mul_f32 v[22:23], v[38:39], v[22:23]
	s_waitcnt vmcnt(9)
	v_pk_fma_f32 v[20:21], v[32:33], v[20:21], v[40:41]
	v_pk_fma_f32 v[22:23], v[34:35], v[22:23], v[42:43]
	v_cvt_pk_bf16_f32 v20, v20, v21
	v_cvt_pk_bf16_f32 v21, v22, v23
	global_store_dwordx2 v[44:45], v[20:21], off
	v_pk_mul_f32 v[24:25], v[24:25], v[46:47] op_sel_hi:[1, 0]
	v_pk_mul_f32 v[26:27], v[26:27], v[46:47] op_sel_hi:[1, 0]
	v_or_b32_e32 v7, 0x800, v4
	v_pk_mul_f32 v[28:29], v[28:29], v[46:47] op_sel_hi:[1, 0]
	v_pk_mul_f32 v[30:31], v[30:31], v[46:47] op_sel_hi:[1, 0]
	v_pk_mul_f32 v[0:1], v[0:1], v[46:47] op_sel_hi:[1, 0]
	v_pk_mul_f32 v[2:3], v[2:3], v[46:47] op_sel_hi:[1, 0]
	v_cmp_eq_u32_e32 vcc, 0, v17
	s_waitcnt vmcnt(9)
	v_pk_mul_f32 v[20:21], v[64:65], v[24:25]
	s_waitcnt vmcnt(8)
	v_pk_add_f32 v[24:25], v[68:69], 1.0 op_sel_hi:[1, 0]
	v_pk_mul_f32 v[22:23], v[66:67], v[26:27]
	v_pk_add_f32 v[26:27], v[70:71], 1.0 op_sel_hi:[1, 0]
	s_waitcnt vmcnt(7)
	v_pk_fma_f32 v[20:21], v[24:25], v[20:21], v[72:73]
	v_pk_fma_f32 v[22:23], v[26:27], v[22:23], v[74:75]
	v_cvt_pk_bf16_f32 v20, v20, v21
	v_cvt_pk_bf16_f32 v21, v22, v23
	global_store_dwordx2 v[44:45], v[20:21], off offset:512
	v_or_b32_e32 v7, 0xc00, v4
	s_waitcnt vmcnt(7)
	v_pk_mul_f32 v[20:21], v[28:29], v[76:77]
	s_waitcnt vmcnt(6)
	v_pk_add_f32 v[24:25], v[80:81], 1.0 op_sel_hi:[1, 0]
	v_pk_mul_f32 v[22:23], v[30:31], v[78:79]
	v_pk_add_f32 v[26:27], v[82:83], 1.0 op_sel_hi:[1, 0]
	s_waitcnt vmcnt(5)
	v_pk_fma_f32 v[20:21], v[20:21], v[24:25], v[84:85]
	v_pk_fma_f32 v[22:23], v[22:23], v[26:27], v[86:87]
	v_cvt_pk_bf16_f32 v20, v20, v21
	v_cvt_pk_bf16_f32 v21, v22, v23
	global_store_dwordx2 v[44:45], v[20:21], off offset:1024
	s_waitcnt vmcnt(5)
	v_pk_mul_f32 v[0:1], v[0:1], v[88:89]
	s_waitcnt vmcnt(4)
	v_pk_add_f32 v[20:21], v[92:93], 1.0 op_sel_hi:[1, 0]
	v_pk_mul_f32 v[2:3], v[2:3], v[90:91]
	v_pk_add_f32 v[22:23], v[94:95], 1.0 op_sel_hi:[1, 0]
	s_waitcnt vmcnt(3)
	v_pk_fma_f32 v[0:1], v[0:1], v[20:21], v[96:97]
	v_pk_fma_f32 v[2:3], v[2:3], v[22:23], v[98:99]
	v_cvt_pk_bf16_f32 v0, v0, v1
	v_cvt_pk_bf16_f32 v1, v2, v3
	global_store_dwordx2 v[44:45], v[0:1], off offset:1536
	s_and_saveexec_b64 s[8:9], vcc
	s_cbranch_execz .LBB0_793
	v_lshlrev_b32_e32 v0, 1, v6
	v_ashrrev_i32_e32 v1, 31, v0
	v_lshl_add_u64 v[0:1], v[0:1], 2, s[6:7]
	global_store_dwordx2 v[0:1], v[18:19], off
	s_branch .LBB0_793

.LBB0_1458:
	s_or_b64 exec, exec, s[2:3]
	v_lshlrev_b32_e32 v66, 3, v109
	v_and_b32_e32 v66, 0x180, v66
	v_and_b32_e32 v68, 0x7f, v107
	v_lshlrev_b32_e32 v0, 9, v112
	s_movk_i32 s2, 0xe000
	v_or_b32_e32 v70, v66, v68
	v_and_or_b32 v67, v106, s2, v0
	v_lshlrev_b32_e32 v0, 2, v70
	v_lshl_add_u64 v[72:73], s[62:63], 0, v[0:1]
	v_add_co_u32_e32 v72, vcc, 0xd000, v72
	v_lshrrev_b32_e32 v0, 3, v107
	s_nop 0
	v_addc_co_u32_e32 v73, vcc, 0, v73, vcc
	v_and_b32_e32 v71, 16, v0
	global_load_dword v128, v[72:73], off offset:2048
	v_or_b32_e32 v129, v71, v67
	v_mov_b64_e32 v[72:73], s[50:51]
	v_mad_i64_i32 v[74:75], s[2:3], v129, s61, v[72:73]
	v_lshlrev_b32_e32 v0, 1, v70
	v_lshl_add_u64 v[76:77], v[74:75], 0, v[0:1]
	global_load_ushort v130, v[76:77], off
	global_load_ushort v131, v[76:77], off offset:1024
	v_or_b32_e32 v76, 1, v129
	v_mad_i64_i32 v[76:77], s[2:3], v76, s61, v[72:73]
	v_lshl_add_u64 v[78:79], v[76:77], 0, v[0:1]
	global_load_ushort v132, v[78:79], off
	global_load_ushort v133, v[78:79], off offset:1024
	v_or_b32_e32 v78, 2, v129
	v_mad_i64_i32 v[78:79], s[2:3], v78, s61, v[72:73]
	v_lshl_add_u64 v[80:81], v[78:79], 0, v[0:1]
	global_load_ushort v134, v[80:81], off
	global_load_ushort v135, v[80:81], off offset:1024
	v_or_b32_e32 v80, 3, v129
	v_mad_i64_i32 v[80:81], s[2:3], v80, s61, v[72:73]
	v_lshl_add_u64 v[82:83], v[80:81], 0, v[0:1]
	global_load_ushort v136, v[82:83], off
	global_load_ushort v137, v[82:83], off offset:1024
	v_or_b32_e32 v82, 4, v129
	v_mad_i64_i32 v[82:83], s[2:3], v82, s61, v[72:73]
	v_lshl_add_u64 v[84:85], v[82:83], 0, v[0:1]
	global_load_ushort v138, v[84:85], off
	global_load_ushort v139, v[84:85], off offset:1024
	v_or_b32_e32 v84, 5, v129
	v_mad_i64_i32 v[84:85], s[2:3], v84, s61, v[72:73]
	v_lshl_add_u64 v[86:87], v[84:85], 0, v[0:1]
	global_load_ushort v140, v[86:87], off
	global_load_ushort v141, v[86:87], off offset:1024
	v_or_b32_e32 v86, 6, v129
	v_mad_i64_i32 v[86:87], s[2:3], v86, s61, v[72:73]
	v_lshl_add_u64 v[88:89], v[86:87], 0, v[0:1]
	global_load_ushort v142, v[88:89], off
	global_load_ushort v143, v[88:89], off offset:1024
	v_or_b32_e32 v88, 7, v129
	v_mad_i64_i32 v[88:89], s[2:3], v88, s61, v[72:73]
	v_lshl_add_u64 v[90:91], v[88:89], 0, v[0:1]
	global_load_ushort v144, v[90:91], off
	global_load_ushort v145, v[90:91], off offset:1024
	v_or_b32_e32 v90, 8, v129
	v_mad_i64_i32 v[90:91], s[2:3], v90, s61, v[72:73]
	v_lshl_add_u64 v[92:93], v[90:91], 0, v[0:1]
	global_load_ushort v146, v[92:93], off
	global_load_ushort v147, v[92:93], off offset:1024
	v_or_b32_e32 v92, 9, v129
	v_mad_i64_i32 v[92:93], s[2:3], v92, s61, v[72:73]
	v_lshl_add_u64 v[94:95], v[92:93], 0, v[0:1]
	global_load_ushort v148, v[94:95], off
	global_load_ushort v149, v[94:95], off offset:1024
	v_or_b32_e32 v94, 10, v129
	v_mad_i64_i32 v[94:95], s[2:3], v94, s61, v[72:73]
	v_lshl_add_u64 v[96:97], v[94:95], 0, v[0:1]
	global_load_ushort v150, v[96:97], off
	global_load_ushort v151, v[96:97], off offset:1024
	v_or_b32_e32 v96, 11, v129
	v_mad_i64_i32 v[96:97], s[2:3], v96, s61, v[72:73]
	v_lshl_add_u64 v[98:99], v[96:97], 0, v[0:1]
	global_load_ushort v152, v[98:99], off
	global_load_ushort v153, v[98:99], off offset:1024
	v_or_b32_e32 v98, 12, v129
	v_mad_i64_i32 v[98:99], s[2:3], v98, s61, v[72:73]
	v_lshl_add_u64 v[100:101], v[98:99], 0, v[0:1]
	global_load_ushort v154, v[100:101], off
	global_load_ushort v155, v[100:101], off offset:1024
	v_or_b32_e32 v100, 13, v129
	v_mad_i64_i32 v[100:101], s[2:3], v100, s61, v[72:73]
	v_lshl_add_u64 v[102:103], v[100:101], 0, v[0:1]
	global_load_ushort v156, v[102:103], off
	global_load_ushort v158, v[102:103], off offset:1024
	v_or_b32_e32 v102, 14, v129
	v_mad_i64_i32 v[102:103], s[2:3], v102, s61, v[72:73]
	v_lshl_add_u64 v[104:105], v[102:103], 0, v[0:1]
	global_load_ushort v162, v[104:105], off
	global_load_ushort v163, v[104:105], off offset:1024
	v_or_b32_e32 v104, 15, v129
	v_mad_i64_i32 v[72:73], s[2:3], v104, s61, v[72:73]
	v_lshl_add_u64 v[104:105], v[72:73], 0, v[0:1]
	v_lshlrev_b32_e32 v0, 1, v66
	global_load_ushort v166, v[104:105], off
	global_load_ushort v167, v[104:105], off offset:1024
	v_lshl_add_u64 v[74:75], v[74:75], 0, v[0:1]
	v_lshlrev_b32_e32 v104, 1, v68
	v_mov_b32_e32 v105, v1
	v_lshl_add_u64 v[72:73], v[72:73], 0, v[0:1]
	v_lshl_add_u64 v[74:75], v[74:75], 0, v[104:105]
	v_lshl_add_u64 v[72:73], v[72:73], 0, v[104:105]
	global_load_ushort v174, v[74:75], off offset:2048
	global_load_ushort v115, v[72:73], off offset:2048
	v_lshl_add_u64 v[74:75], v[76:77], 0, v[0:1]
	v_lshl_add_u64 v[74:75], v[74:75], 0, v[104:105]
	global_load_ushort v175, v[74:75], off offset:2048
	v_lshl_add_u64 v[74:75], v[78:79], 0, v[0:1]
	v_lshl_add_u64 v[74:75], v[74:75], 0, v[104:105]
	global_load_ushort v176, v[74:75], off offset:2048
	v_lshl_add_u64 v[74:75], v[80:81], 0, v[0:1]
	v_lshl_add_u64 v[74:75], v[74:75], 0, v[104:105]
	global_load_ushort v177, v[74:75], off offset:2048
	v_lshl_add_u64 v[74:75], v[82:83], 0, v[0:1]
	v_lshl_add_u64 v[74:75], v[74:75], 0, v[104:105]
	global_load_ushort v178, v[74:75], off offset:2048
	v_lshl_add_u64 v[74:75], v[84:85], 0, v[0:1]
	v_lshl_add_u64 v[74:75], v[74:75], 0, v[104:105]
	global_load_ushort v179, v[74:75], off offset:2048
	v_lshl_add_u64 v[74:75], v[86:87], 0, v[0:1]
	v_lshl_add_u64 v[74:75], v[74:75], 0, v[104:105]
	global_load_ushort v180, v[74:75], off offset:2048
	v_lshl_add_u64 v[74:75], v[88:89], 0, v[0:1]
	v_lshl_add_u64 v[74:75], v[74:75], 0, v[104:105]
	global_load_ushort v181, v[74:75], off offset:2048
	v_lshl_add_u64 v[74:75], v[90:91], 0, v[0:1]
	v_lshl_add_u64 v[74:75], v[74:75], 0, v[104:105]
	global_load_ushort v182, v[74:75], off offset:2048
	v_lshl_add_u64 v[74:75], v[92:93], 0, v[0:1]
	v_lshl_add_u64 v[74:75], v[74:75], 0, v[104:105]
	global_load_ushort v183, v[74:75], off offset:2048
	v_lshl_add_u64 v[74:75], v[94:95], 0, v[0:1]
	v_lshl_add_u64 v[74:75], v[74:75], 0, v[104:105]
	global_load_ushort v184, v[74:75], off offset:2048
	v_lshl_add_u64 v[74:75], v[96:97], 0, v[0:1]
	v_lshl_add_u64 v[74:75], v[74:75], 0, v[104:105]
	global_load_ushort v185, v[74:75], off offset:2048
	v_lshl_add_u64 v[74:75], v[98:99], 0, v[0:1]
	v_lshl_add_u64 v[74:75], v[74:75], 0, v[104:105]
	global_load_ushort v186, v[74:75], off offset:2048
	v_lshl_add_u64 v[74:75], v[100:101], 0, v[0:1]
	v_lshl_add_u64 v[74:75], v[74:75], 0, v[104:105]
	global_load_ushort v187, v[74:75], off offset:2048
	v_lshl_add_u64 v[74:75], v[102:103], 0, v[0:1]
	v_lshl_add_u64 v[74:75], v[74:75], 0, v[104:105]
	global_load_ushort v188, v[74:75], off offset:2048
	v_mul_u32_u24_e32 v72, 40, v68
	v_lshl_add_u32 v77, v72, 1, s0
	v_lshl_add_u64 v[72:73], s[50:51], 0, v[0:1]
	v_lshrrev_b32_e32 v0, 1, v107
	v_and_b32_e32 v69, 31, v107
	v_and_b32_e32 v78, 0x60, v0
	v_mov_b32_e32 v76, s0
	v_lshlrev_b32_e32 v0, 1, v78
	v_or_b32_e32 v79, v78, v69
	s_movk_i32 s2, 0x80
	v_lshl_add_u64 v[74:75], v[72:73], 0, v[0:1]
	v_lshlrev_b32_e32 v0, 1, v110
	v_mad_u32_u24 v76, v79, s97, v76
	v_and_b32_e32 v81, 64, v202
	v_cmp_gt_u32_e64 s[2:3], s2, v108
	v_lshl_add_u64 v[108:109], v[74:75], 0, v[0:1]
	v_add_u32_e32 v161, v76, v0
	v_xor_b32_e32 v0, 32, v202
	v_add_u32_e32 v81, 64, v81
	v_cmp_lt_i32_e32 vcc, v0, v81
	v_readlane_b32 s40, v240, 0
	v_readlane_b32 s41, v240, 1
	v_cndmask_b32_e32 v0, v202, v0, vcc
	v_lshlrev_b32_e32 v164, 2, v0
	v_mul_u32_u24_e32 v0, 0x88, v71
	v_or_b32_e32 v0, v0, v68
	v_lshl_add_u32 v165, v0, 1, s0
	v_or_b32_e32 v0, 2, v110
	v_cmp_gt_u32_e64 s[10:11], v0, v69
	v_or_b32_e32 v0, 3, v110
	v_cmp_gt_u32_e64 s[12:13], v0, v69
	v_or_b32_e32 v0, 8, v110
	v_cmp_gt_u32_e64 s[14:15], v0, v69
	v_or_b32_e32 v0, 9, v110
	v_cmp_gt_u32_e64 s[16:17], v0, v69
	v_or_b32_e32 v0, 10, v110
	v_cmp_gt_u32_e64 s[18:19], v0, v69
	v_or_b32_e32 v0, 11, v110
	v_cmp_gt_u32_e64 s[20:21], v0, v69
	v_or_b32_e32 v0, 16, v110
	v_cmp_gt_u32_e64 s[22:23], v0, v69
	v_or_b32_e32 v0, 17, v110
	v_cmp_gt_u32_e64 s[24:25], v0, v69
	v_or_b32_e32 v0, 18, v110
	v_cmp_gt_u32_e64 s[26:27], v0, v69
	v_or_b32_e32 v0, 19, v110
	v_cmp_gt_u32_e64 s[28:29], v0, v69
	v_or_b32_e32 v0, 24, v110
	s_load_dwordx2 s[40:41], s[40:41], 0x40
	v_cmp_gt_u32_e64 s[30:31], v0, v69
	v_or_b32_e32 v0, 25, v110
	v_cmp_gt_u32_e64 s[34:35], v0, v69
	v_or_b32_e32 v0, 26, v110
	v_mul_u32_u24_e32 v74, 0x88, v69
	v_or_b32_e32 v78, v110, v78
	v_cmp_gt_u32_e64 s[36:37], v0, v69
	v_or_b32_e32 v0, 27, v110
	v_lshl_add_u32 v74, v74, 1, s0
	v_lshlrev_b32_e32 v159, 3, v111
	v_lshlrev_b32_e32 v75, 4, v111
	v_cmp_gt_u32_e64 s[38:39], v0, v69
	v_lshlrev_b32_e32 v0, 2, v78
	s_waitcnt vmcnt(48)
	v_sub_f32_e32 v106, 1.0, v128
	v_lshl_add_u32 v157, v71, 1, v77
	v_add_u32_e32 v160, v74, v75
	v_sub_u32_e32 v80, 0, v159
	v_add_u32_e32 v75, s0, v75
	v_cmp_eq_u32_e64 s[4:5], 0, v111
	v_mul_i32_i24_e32 v81, 0xfffffef4, v69
	v_mul_i32_i24_e32 v82, 0xffffffb4, v68
	v_mul_i32_i24_e32 v79, 0xffffffb4, v79
	v_cmp_gt_u32_e64 s[6:7], v110, v69
	v_cmp_lt_u32_e64 s[8:9], v110, v69
	v_mul_u32_u24_e32 v71, 0x50, v69
	s_waitcnt lgkmcnt(0)
	v_lshl_add_u64 v[110:111], s[40:41], 0, v[0:1]
	v_lshlrev_b32_e32 v0, 1, v78
	s_mov_b32 s44, 0
	v_lshl_add_u64 v[112:113], v[72:73], 0, v[0:1]
	v_mov_b32_e32 v107, v106
	v_or_b32_e32 v168, v67, v69
	v_lshlrev_b32_e32 v0, 1, v70
	v_lshlrev_b32_e32 v114, 1, v66
	v_lshlrev_b32_e32 v116, 1, v68
	v_add_u32_e32 v169, v160, v80
	v_add_u32_e32 v170, v75, v71
	v_add_u32_e32 v171, v76, v79
	v_add_u32_e32 v172, v74, v81
	v_add_u32_e32 v173, v77, v82
	global_load_dwordx4 v[222:225], v[110:111], off offset:512
	global_load_dwordx4 v[226:229], v[110:111], off offset:544
	global_load_dwordx4 v[230:233], v[110:111], off offset:576
	global_load_dwordx4 v[234:237], v[110:111], off offset:608
	s_branch .LBB0_1461

.LBB0_1467:
	v_add_u32_e32 v84, 0xbc00, v172
	ds_read2_b32 v[82:83], v84 offset1:32
	v_mad_i64_i32 v[88:89], s[40:41], v117, s61, 0
	s_waitcnt lgkmcnt(0)
	v_add_f32_e32 v85, v82, v83
	ds_read2_b32 v[82:83], v84 offset0:64 offset1:96
	s_waitcnt lgkmcnt(0)
	v_add_f32_e32 v82, v85, v82
	v_mov_b64_e32 v[84:85], v[222:223]
	v_mov_b64_e32 v[86:87], v[224:225]
	v_add_f32_e32 v82, v82, v83
	v_fmamk_f32 v82, v82, 0x3c000000, v201
	v_cmp_gt_f32_e32 vcc, s46, v82
	v_mul_f32_e32 v83, 0x4b800000, v82
	s_nop 0
	v_cndmask_b32_e32 v82, v82, v83, vcc
	v_rsq_f32_e32 v82, v82
	s_nop 0
	v_mul_f32_e32 v83, 0x45800000, v82
	v_cndmask_b32_e32 v82, v82, v83, vcc
	v_pk_mul_f32 v[66:67], v[66:67], v[82:83] op_sel_hi:[1,0]
	v_pk_mul_f32 v[68:69], v[68:69], v[82:83] op_sel_hi:[1,0]
	v_pk_mul_f32 v[70:71], v[70:71], v[82:83] op_sel_hi:[1,0]
	s_waitcnt vmcnt(0)
	v_pk_mul_f32 v[66:67], v[84:85], v[66:67]
	v_lshlrev_b32_e32 v84, 16, v124
	v_and_b32_e32 v85, 0xffff0000, v124
	v_pk_mul_f32 v[66:67], v[66:67], v[84:85]
	v_pk_mul_f32 v[68:69], v[86:87], v[68:69]
	v_lshlrev_b32_e32 v84, 16, v125
	v_and_b32_e32 v85, 0xffff0000, v125
	v_pk_mul_f32 v[68:69], v[68:69], v[84:85]
	v_cvt_pk_bf16_f32 v66, v66, v67
	v_cvt_pk_bf16_f32 v67, v68, v69
	v_lshl_add_u64 v[84:85], v[112:113], 0, v[88:89]
	global_store_dwordx2 v[84:85], v[66:67], off offset:3072
	v_mov_b64_e32 v[66:67], v[226:227]
	v_mov_b64_e32 v[68:69], v[228:229]
	v_pk_mul_f32 v[66:67], v[66:67], v[70:71]
	v_lshlrev_b32_e32 v70, 16, v122
	v_and_b32_e32 v71, 0xffff0000, v122
	v_pk_mul_f32 v[66:67], v[66:67], v[70:71]
	v_pk_mul_f32 v[70:71], v[72:73], v[82:83] op_sel_hi:[1,0]
	v_cvt_pk_bf16_f32 v66, v66, v67
	v_pk_mul_f32 v[68:69], v[70:71], v[68:69]
	v_lshlrev_b32_e32 v70, 16, v123
	v_and_b32_e32 v71, 0xffff0000, v123
	v_pk_mul_f32 v[68:69], v[68:69], v[70:71]
	v_pk_mul_f32 v[70:71], v[74:75], v[82:83] op_sel_hi:[1,0]
	v_cvt_pk_bf16_f32 v67, v68, v69
	global_store_dwordx2 v[84:85], v[66:67], off offset:3088
	v_mov_b64_e32 v[66:67], v[230:231]
	v_mov_b64_e32 v[68:69], v[232:233]
	v_pk_mul_f32 v[66:67], v[70:71], v[66:67]
	v_lshlrev_b32_e32 v70, 16, v120
	v_and_b32_e32 v71, 0xffff0000, v120
	v_pk_mul_f32 v[66:67], v[66:67], v[70:71]
	v_pk_mul_f32 v[70:71], v[76:77], v[82:83] op_sel_hi:[1,0]
	v_cvt_pk_bf16_f32 v66, v66, v67
	v_pk_mul_f32 v[68:69], v[70:71], v[68:69]
	v_lshlrev_b32_e32 v70, 16, v121
	v_and_b32_e32 v71, 0xffff0000, v121
	v_pk_mul_f32 v[68:69], v[68:69], v[70:71]
	v_pk_mul_f32 v[70:71], v[78:79], v[82:83] op_sel_hi:[1,0]
	v_cvt_pk_bf16_f32 v67, v68, v69
	global_store_dwordx2 v[84:85], v[66:67], off offset:3104
	v_mov_b64_e32 v[66:67], v[234:235]
	v_mov_b64_e32 v[68:69], v[236:237]
	v_pk_mul_f32 v[66:67], v[70:71], v[66:67]
	v_lshlrev_b32_e32 v70, 16, v118
	v_and_b32_e32 v71, 0xffff0000, v118
	v_pk_mul_f32 v[66:67], v[66:67], v[70:71]
	v_pk_mul_f32 v[70:71], v[80:81], v[82:83] op_sel_hi:[1,0]
	v_cvt_pk_bf16_f32 v66, v66, v67
	v_pk_mul_f32 v[68:69], v[70:71], v[68:69]
	v_lshlrev_b32_e32 v70, 16, v119
	v_and_b32_e32 v71, 0xffff0000, v119
	v_pk_mul_f32 v[68:69], v[68:69], v[70:71]
	s_nop 0
	v_cvt_pk_bf16_f32 v67, v68, v69
	global_store_dwordx2 v[84:85], v[66:67], off offset:3120
	s_add_i32 s44, s44, 32
	s_cmpk_lg_i32 s44, 0x200
	s_cbranch_scc1 .LBB0_1461
